# v8 with all device code shifted by one 4-byte s_nop at kernel entry (code placement test)
# baseline (speedup 1.0000x reference)
; #define LAS __attribute__((address_space(3)))
; __device__ __forceinline__ unsigned xb_add(unsigned* p, unsigned v) { return __hip_atomic_fetch_add(p, v, __ATOMIC_RELAXED, __HIP_MEMORY_SCOPE_AGENT); }
; __device__ __forceinline__ unsigned xb_xcc_id() { return (unsigned)__builtin_amdgcn_s_getreg((3 << 11) | 20) & 0xFu; }
; __device__ __forceinline__ XcdBarrier xcd_barrier_post(unsigned* bar, volatile LAS unsigned* st, int wave) {
;     XcdBarrier b; b.bar = bar; b.x = xb_xcc_id(); b.st = st; b.wave = wave;
;     if (threadIdx.x == 0) (void)xb_add(&bar[XB_XCNT(b.x)], 1u);
;     return b;
; __global__ void __launch_bounds__(NTHREADS, 2) hybrid_fwd(Args args) {
;     extern __shared__ __attribute__((aligned(16))) unsigned char lds_raw[];
;     Frame F;
;     F.lds = (LAS unsigned char*)lds_raw;
;     F.MISC = (volatile LAS unsigned*)(F.lds + MISC_OFF);
;     F.tid = threadIdx.x; F.lane = F.tid & 63; F.wave = __builtin_amdgcn_readfirstlane(F.tid >> 6);
;     F.G = gridDim.x; F.ws = args.ws;
;     if (F.tid < 64) F.MISC[F.tid] = 0u;
;     __syncthreads();
;     unsigned* ctl = (unsigned*)(F.ws + WS_CTL);
;     ...
;     const XcdBarrier bar = xcd_barrier_post(ctl + CW_BAR, F.MISC + 8, F.wave);
_Z10hybrid_fwd4Args:
	s_nop 0
	s_load_dwordx4 s[92:95], s[0:1], 0xc0
	s_load_dword s33, s[0:1], 0xd0
	s_mov_b32 s73, s2
	s_add_u32 s2, s0, 0xd0
	s_addc_u32 s3, s1, 0
	v_readfirstlane_b32 s72, v0
	v_writelane_b32 v247, s2, 0
	v_cmp_gt_u32_e32 vcc, 64, v0
	s_nop 0
	v_writelane_b32 v247, s3, 1
	s_and_saveexec_b64 s[2:3], vcc
	v_lshl_add_u32 v1, v0, 2, 0
	v_add_u32_e32 v1, 0x23f00, v1
	v_mov_b32_e32 v2, 0
	ds_write_b32 v1, v2
	s_or_b64 exec, exec, s[2:3]
	s_load_dwordx16 s[76:91], s[0:1], 0x0
	s_waitcnt lgkmcnt(0)
	s_add_u32 s2, s92, 0x4000
	s_addc_u32 s3, s93, 0
	v_writelane_b32 v247, s2, 2
	s_barrier
	s_nop 0
	v_writelane_b32 v247, s3, 3
	s_getreg_b32 s2, hwreg(HW_REG_XCC_ID, 0, 4)
	s_and_b32 s2, s2, 15
	v_cmp_eq_u32_e32 vcc, 0, v0
	v_writelane_b32 v247, s2, 4
	s_and_saveexec_b64 s[2:3], vcc
	s_cbranch_execz .LBB0_5
	s_mov_b64 s[4:5], exec
	v_mbcnt_lo_u32_b32 v0, s4, 0
	v_mbcnt_hi_u32_b32 v0, s5, v0
	v_cmp_eq_u32_e32 vcc, 0, v0
	s_and_b64 s[6:7], exec, vcc
	s_mov_b64 exec, s[6:7]
	s_cbranch_execz .LBB0_5
	v_readlane_b32 s6, v247, 4
	s_bcnt1_i32_b64 s4, s[4:5]
	s_lshl_b32 s6, s6, 8
	v_mov_b32_e32 v1, s4
	v_readlane_b32 s4, v247, 2
	v_mov_b32_e32 v0, s6
	v_readlane_b32 s5, v247, 3
	s_nop 4
	global_atomic_add v0, v1, s[4:5] offset:1024
